# SwiGLU epilogue: store addresses beyond the first formed with one 64-bit add (constant in a dead SGPR pair) instead of v_add_co/v_addc pairs with hazard pads
# baseline (speedup 1.0000x reference)
.LBB0_77:
	s_add_u32 s6, s26, s50
	s_addc_u32 s19, s27, s51
	s_add_u32 s6, s6, 0x100
	s_addc_u32 s19, s19, 0
	s_add_u32 s23, s10, s50
	s_addc_u32 s52, s11, s51
	s_add_i32 s82, 0, 0x10000
	v_add_u32_e32 v146, s82, v154
	ds_read_b128 v[158:161], v146
	ds_read_b128 v[162:165], v146 offset:1024
	ds_read_b128 v[166:169], v146 offset:2048
	ds_read_b128 v[170:173], v146 offset:3072
	s_cmpk_eq_i32 s50, 0x700
	s_cselect_b32 s55, s12, s19
	s_cselect_b32 s54, s31, s6
	s_cselect_b32 s53, s35, s52
	s_cselect_b32 s52, s39, s23
	v_lshl_add_u64 v[146:147], v[150:151], 0, s[50:51]
	s_add_i32 m0, s68, 0xc000
	ds_read_b128 v[174:177], v157
	ds_read_b128 v[178:181], v157 offset:1024
	ds_read_b128 v[182:185], v157 offset:2048
	ds_read_b128 v[206:209], v157 offset:3072
	ds_read_b128 v[210:213], v157 offset:4096
	ds_read_b128 v[214:217], v157 offset:5120
	ds_read_b128 v[218:221], v157 offset:6144
	ds_read_b128 v[222:225], v157 offset:7168
	global_load_lds_dwordx4 v[146:147], off
	v_lshl_add_u64 v[146:147], v[152:153], 0, s[50:51]
	s_add_i32 m0, s68, 0xe000
	s_nop 0
	global_load_lds_dwordx4 v[146:147], off
	s_add_i32 s6, 0, 0x14000
	v_add_u32_e32 v146, s6, v154
	ds_read_b128 v[226:229], v146
	ds_read_b128 v[230:233], v146 offset:1024
	ds_read_b128 v[234:237], v146 offset:2048
	ds_read_b128 v[238:241], v146 offset:3072
	s_nop 0
	s_waitcnt vmcnt(8)
	s_waitcnt lgkmcnt(0)
	s_barrier
	v_mfma_f32_16x16x32_bf16 v[124:127], v[158:161], v[174:177], v[124:127]
	v_mfma_f32_16x16x32_bf16 v[120:123], v[166:169], v[174:177], v[120:123]
	v_mfma_f32_16x16x32_bf16 v[116:119], v[158:161], v[182:185], v[116:119]
	v_mfma_f32_16x16x32_bf16 v[112:115], v[166:169], v[182:185], v[112:115]
	v_mfma_f32_16x16x32_bf16 v[108:111], v[158:161], v[210:213], v[108:111]
	v_mfma_f32_16x16x32_bf16 v[104:107], v[166:169], v[210:213], v[104:107]
	v_mfma_f32_16x16x32_bf16 v[100:103], v[158:161], v[218:221], v[100:103]
	v_mfma_f32_16x16x32_bf16 v[96:99], v[166:169], v[218:221], v[96:99]
	v_mfma_f32_16x16x32_bf16 v[124:127], v[162:165], v[178:181], v[124:127]
	v_mfma_f32_16x16x32_bf16 v[120:123], v[170:173], v[178:181], v[120:123]
	v_mfma_f32_16x16x32_bf16 v[116:119], v[162:165], v[206:209], v[116:119]
	v_mfma_f32_16x16x32_bf16 v[112:115], v[170:173], v[206:209], v[112:115]
	v_mfma_f32_16x16x32_bf16 v[108:111], v[162:165], v[214:217], v[108:111]
	v_mfma_f32_16x16x32_bf16 v[104:107], v[170:173], v[214:217], v[104:107]
	v_mfma_f32_16x16x32_bf16 v[100:103], v[162:165], v[222:225], v[100:103]
	v_mfma_f32_16x16x32_bf16 v[96:99], v[170:173], v[222:225], v[96:99]
	v_mfma_f32_16x16x32_bf16 v[92:95], v[226:229], v[174:177], v[92:95]
	v_mfma_f32_16x16x32_bf16 v[88:91], v[234:237], v[174:177], v[88:91]
	v_mfma_f32_16x16x32_bf16 v[84:87], v[226:229], v[182:185], v[84:87]
	v_mfma_f32_16x16x32_bf16 v[80:83], v[234:237], v[182:185], v[80:83]
	v_mfma_f32_16x16x32_bf16 v[76:79], v[226:229], v[210:213], v[76:79]
	v_mfma_f32_16x16x32_bf16 v[72:75], v[234:237], v[210:213], v[72:75]
	v_mfma_f32_16x16x32_bf16 v[68:71], v[226:229], v[218:221], v[68:71]
	v_mfma_f32_16x16x32_bf16 v[64:67], v[234:237], v[218:221], v[64:67]
	v_mfma_f32_16x16x32_bf16 v[92:95], v[230:233], v[178:181], v[92:95]
	v_mfma_f32_16x16x32_bf16 v[88:91], v[238:241], v[178:181], v[88:91]
	v_mfma_f32_16x16x32_bf16 v[84:87], v[230:233], v[206:209], v[84:87]
	v_mfma_f32_16x16x32_bf16 v[80:83], v[238:241], v[206:209], v[80:83]
	v_mfma_f32_16x16x32_bf16 v[76:79], v[230:233], v[214:217], v[76:79]
	v_mfma_f32_16x16x32_bf16 v[72:75], v[238:241], v[214:217], v[72:75]
	v_mfma_f32_16x16x32_bf16 v[68:71], v[230:233], v[222:225], v[68:71]
	v_mfma_f32_16x16x32_bf16 v[64:67], v[238:241], v[222:225], v[64:67]
	s_barrier
	s_add_i32 s19, s82, s59
	v_lshl_add_u64 v[146:147], s[52:53], 0, v[140:141]
	s_mov_b32 m0, s19
	v_lshl_add_u64 v[148:149], s[52:53], 0, v[132:133]
	global_load_lds_dwordx4 v[146:147], off
	s_add_i32 m0, s19, 0x2000
	s_nop 0
	global_load_lds_dwordx4 v[148:149], off
	s_mov_b32 m0, s68
	v_lshl_add_u64 v[194:195], s[54:55], 0, v[128:129]
	ds_read_b128 v[174:177], v157 offset:16384
	ds_read_b128 v[178:181], v157 offset:17408
	ds_read_b128 v[182:185], v157 offset:18432
	ds_read_b128 v[206:209], v157 offset:19456
	ds_read_b128 v[210:213], v157 offset:20480
	ds_read_b128 v[214:217], v157 offset:21504
	ds_read_b128 v[218:221], v157 offset:22528
	ds_read_b128 v[222:225], v157 offset:23552
	global_load_lds_dwordx4 v[194:195], off
	v_lshl_add_u64 v[196:197], s[54:55], 0, v[130:131]
	s_mov_b32 m0, s69
	s_nop 0
	global_load_lds_dwordx4 v[196:197], off
	s_add_u32 s82, s52, 0x40000
	s_addc_u32 s83, s53, 0
	s_add_i32 s6, s6, s59
	v_lshl_add_u64 v[250:251], s[82:83], 0, v[140:141]
	s_mov_b32 m0, s6
	s_nop 0
	global_load_lds_dwordx4 v[250:251], off
	v_lshl_add_u64 v[250:251], s[82:83], 0, v[132:133]
	s_add_i32 m0, s6, 0x2000
	s_nop 0
	global_load_lds_dwordx4 v[250:251], off
	s_nop 0
	s_waitcnt vmcnt(8)
	s_waitcnt lgkmcnt(0)
	s_barrier
	v_mfma_f32_16x16x32_bf16 v[60:63], v[158:161], v[174:177], v[60:63]
	v_mfma_f32_16x16x32_bf16 v[56:59], v[166:169], v[174:177], v[56:59]
	v_mfma_f32_16x16x32_bf16 v[52:55], v[158:161], v[182:185], v[52:55]
	v_mfma_f32_16x16x32_bf16 v[48:51], v[166:169], v[182:185], v[48:51]
	v_mfma_f32_16x16x32_bf16 v[44:47], v[158:161], v[210:213], v[44:47]
	v_mfma_f32_16x16x32_bf16 v[40:43], v[166:169], v[210:213], v[40:43]
	v_mfma_f32_16x16x32_bf16 v[36:39], v[158:161], v[218:221], v[36:39]
	v_mfma_f32_16x16x32_bf16 v[32:35], v[166:169], v[218:221], v[32:35]
	v_mfma_f32_16x16x32_bf16 v[60:63], v[162:165], v[178:181], v[60:63]
	v_mfma_f32_16x16x32_bf16 v[56:59], v[170:173], v[178:181], v[56:59]
	v_mfma_f32_16x16x32_bf16 v[52:55], v[162:165], v[206:209], v[52:55]
	v_mfma_f32_16x16x32_bf16 v[48:51], v[170:173], v[206:209], v[48:51]
	v_mfma_f32_16x16x32_bf16 v[44:47], v[162:165], v[214:217], v[44:47]
	v_mfma_f32_16x16x32_bf16 v[40:43], v[170:173], v[214:217], v[40:43]
	v_mfma_f32_16x16x32_bf16 v[36:39], v[162:165], v[222:225], v[36:39]
	v_mfma_f32_16x16x32_bf16 v[32:35], v[170:173], v[222:225], v[32:35]
	v_mfma_f32_16x16x32_bf16 v[28:31], v[226:229], v[174:177], v[28:31]
	v_mfma_f32_16x16x32_bf16 v[24:27], v[234:237], v[174:177], v[24:27]
	v_mfma_f32_16x16x32_bf16 v[20:23], v[226:229], v[182:185], v[20:23]
	v_mfma_f32_16x16x32_bf16 v[16:19], v[234:237], v[182:185], v[16:19]
	v_mfma_f32_16x16x32_bf16 v[12:15], v[226:229], v[210:213], v[12:15]
	v_mfma_f32_16x16x32_bf16 v[8:11], v[234:237], v[210:213], v[8:11]
	v_mfma_f32_16x16x32_bf16 v[4:7], v[226:229], v[218:221], v[4:7]
	v_mfma_f32_16x16x32_bf16 v[0:3], v[234:237], v[218:221], v[0:3]
	v_mfma_f32_16x16x32_bf16 v[28:31], v[230:233], v[178:181], v[28:31]
	v_mfma_f32_16x16x32_bf16 v[24:27], v[238:241], v[178:181], v[24:27]
	v_mfma_f32_16x16x32_bf16 v[20:23], v[230:233], v[206:209], v[20:23]
	v_mfma_f32_16x16x32_bf16 v[16:19], v[238:241], v[206:209], v[16:19]
	v_mfma_f32_16x16x32_bf16 v[12:15], v[230:233], v[214:217], v[12:15]
	v_mfma_f32_16x16x32_bf16 v[8:11], v[238:241], v[214:217], v[8:11]
	v_mfma_f32_16x16x32_bf16 v[4:7], v[230:233], v[222:225], v[4:7]
	v_mfma_f32_16x16x32_bf16 v[0:3], v[238:241], v[222:225], v[0:3]
	s_barrier
	s_add_i32 s6, 0, 0x18000
	v_add_u32_e32 v170, s6, v154
	ds_read_b128 v[158:161], v170
	ds_read_b128 v[162:165], v170 offset:1024
	ds_read_b128 v[166:169], v170 offset:2048
	ds_read_b128 v[170:173], v170 offset:3072
	s_add_u32 s54, s54, 0x40000
	s_addc_u32 s55, s55, 0
	s_mov_b32 m0, s70
	v_lshl_add_u64 v[226:227], s[54:55], 0, v[128:129]
	ds_read_b128 v[174:177], v157 offset:32768
	ds_read_b128 v[178:181], v157 offset:33792
	ds_read_b128 v[182:185], v157 offset:34816
	ds_read_b128 v[206:209], v157 offset:35840
	ds_read_b128 v[210:213], v157 offset:36864
	ds_read_b128 v[214:217], v157 offset:37888
	ds_read_b128 v[218:221], v157 offset:38912
	ds_read_b128 v[222:225], v157 offset:39936
	global_load_lds_dwordx4 v[226:227], off
	v_lshl_add_u64 v[226:227], s[54:55], 0, v[130:131]
	s_mov_b32 m0, s71
	s_nop 0
	global_load_lds_dwordx4 v[226:227], off
	s_add_i32 s19, 0, 0x1c000
	v_add_u32_e32 v192, s19, v154
	ds_read_b128 v[226:229], v192
	ds_read_b128 v[230:233], v192 offset:1024
	ds_read_b128 v[234:237], v192 offset:2048
	ds_read_b128 v[238:241], v192 offset:3072
	s_waitcnt vmcnt(8)
	s_waitcnt lgkmcnt(0)
	s_barrier
	v_mfma_f32_16x16x32_bf16 v[124:127], v[158:161], v[174:177], v[124:127]
	v_mfma_f32_16x16x32_bf16 v[120:123], v[166:169], v[174:177], v[120:123]
	v_mfma_f32_16x16x32_bf16 v[116:119], v[158:161], v[182:185], v[116:119]
	v_mfma_f32_16x16x32_bf16 v[112:115], v[166:169], v[182:185], v[112:115]
	v_mfma_f32_16x16x32_bf16 v[108:111], v[158:161], v[210:213], v[108:111]
	v_mfma_f32_16x16x32_bf16 v[104:107], v[166:169], v[210:213], v[104:107]
	v_mfma_f32_16x16x32_bf16 v[100:103], v[158:161], v[218:221], v[100:103]
	v_mfma_f32_16x16x32_bf16 v[96:99], v[166:169], v[218:221], v[96:99]
	v_mfma_f32_16x16x32_bf16 v[124:127], v[162:165], v[178:181], v[124:127]
	v_mfma_f32_16x16x32_bf16 v[120:123], v[170:173], v[178:181], v[120:123]
	v_mfma_f32_16x16x32_bf16 v[116:119], v[162:165], v[206:209], v[116:119]
	v_mfma_f32_16x16x32_bf16 v[112:115], v[170:173], v[206:209], v[112:115]
	v_mfma_f32_16x16x32_bf16 v[108:111], v[162:165], v[214:217], v[108:111]
	v_mfma_f32_16x16x32_bf16 v[104:107], v[170:173], v[214:217], v[104:107]
	v_mfma_f32_16x16x32_bf16 v[100:103], v[162:165], v[222:225], v[100:103]
	v_mfma_f32_16x16x32_bf16 v[96:99], v[170:173], v[222:225], v[96:99]
	v_mfma_f32_16x16x32_bf16 v[92:95], v[226:229], v[174:177], v[92:95]
	v_mfma_f32_16x16x32_bf16 v[88:91], v[234:237], v[174:177], v[88:91]
	v_mfma_f32_16x16x32_bf16 v[84:87], v[226:229], v[182:185], v[84:87]
	v_mfma_f32_16x16x32_bf16 v[80:83], v[234:237], v[182:185], v[80:83]
	v_mfma_f32_16x16x32_bf16 v[76:79], v[226:229], v[210:213], v[76:79]
	v_mfma_f32_16x16x32_bf16 v[72:75], v[234:237], v[210:213], v[72:75]
	v_mfma_f32_16x16x32_bf16 v[68:71], v[226:229], v[218:221], v[68:71]
	v_mfma_f32_16x16x32_bf16 v[64:67], v[234:237], v[218:221], v[64:67]
	v_mfma_f32_16x16x32_bf16 v[92:95], v[230:233], v[178:181], v[92:95]
	v_mfma_f32_16x16x32_bf16 v[88:91], v[238:241], v[178:181], v[88:91]
	v_mfma_f32_16x16x32_bf16 v[84:87], v[230:233], v[206:209], v[84:87]
	v_mfma_f32_16x16x32_bf16 v[80:83], v[238:241], v[206:209], v[80:83]
	v_mfma_f32_16x16x32_bf16 v[76:79], v[230:233], v[214:217], v[76:79]
	v_mfma_f32_16x16x32_bf16 v[72:75], v[238:241], v[214:217], v[72:75]
	v_mfma_f32_16x16x32_bf16 v[68:71], v[230:233], v[222:225], v[68:71]
	v_mfma_f32_16x16x32_bf16 v[64:67], v[238:241], v[222:225], v[64:67]
	s_barrier
	s_add_i32 s6, s6, s59
	v_lshl_add_u64 v[146:147], v[146:147], 0, s[36:37]
	s_mov_b32 m0, s6
	s_nop 0
	global_load_lds_dwordx4 v[146:147], off
	v_lshl_add_u64 v[146:147], v[148:149], 0, s[36:37]
	s_add_i32 m0, s6, 0x2000
	s_nop 0
	global_load_lds_dwordx4 v[146:147], off
	s_mov_b32 m0, s72
	v_lshl_add_u64 v[146:147], v[194:195], 0, s[36:37]
	ds_read_b128 v[174:177], v157 offset:49152
	ds_read_b128 v[178:181], v157 offset:50176
	ds_read_b128 v[182:185], v157 offset:51200
	ds_read_b128 v[206:209], v157 offset:52224
	ds_read_b128 v[210:213], v157 offset:53248
	ds_read_b128 v[214:217], v157 offset:54272
	ds_read_b128 v[218:221], v157 offset:55296
	ds_read_b128 v[222:225], v157 offset:56320
	global_load_lds_dwordx4 v[146:147], off
	v_lshl_add_u64 v[146:147], v[196:197], 0, s[36:37]
	s_mov_b32 m0, s73
	s_nop 0
	global_load_lds_dwordx4 v[146:147], off
	s_add_u32 s52, s52, 0x40080
	s_addc_u32 s53, s53, 0
	s_add_i32 s6, s19, s59
	v_lshl_add_u64 v[146:147], s[52:53], 0, v[140:141]
	s_mov_b32 m0, s6
	s_nop 0
	global_load_lds_dwordx4 v[146:147], off
	v_lshl_add_u64 v[146:147], s[52:53], 0, v[132:133]
	s_add_i32 m0, s6, 0x2000
	s_nop 0
	global_load_lds_dwordx4 v[146:147], off
	s_add_i32 s81, s81, 2
	s_add_u32 s50, s50, 0x100
	s_addc_u32 s51, s51, 0
	s_cmp_gt_u32 s81, 13
	s_nop 0
	s_waitcnt vmcnt(8)
	s_waitcnt lgkmcnt(0)
	s_barrier
	v_mfma_f32_16x16x32_bf16 v[60:63], v[158:161], v[174:177], v[60:63]
	v_mfma_f32_16x16x32_bf16 v[56:59], v[166:169], v[174:177], v[56:59]
	v_mfma_f32_16x16x32_bf16 v[52:55], v[158:161], v[182:185], v[52:55]
	v_mfma_f32_16x16x32_bf16 v[48:51], v[166:169], v[182:185], v[48:51]
	v_mfma_f32_16x16x32_bf16 v[44:47], v[158:161], v[210:213], v[44:47]
	v_mfma_f32_16x16x32_bf16 v[40:43], v[166:169], v[210:213], v[40:43]
	v_mfma_f32_16x16x32_bf16 v[36:39], v[158:161], v[218:221], v[36:39]
	v_mfma_f32_16x16x32_bf16 v[32:35], v[166:169], v[218:221], v[32:35]
	v_mfma_f32_16x16x32_bf16 v[60:63], v[162:165], v[178:181], v[60:63]
	v_mfma_f32_16x16x32_bf16 v[56:59], v[170:173], v[178:181], v[56:59]
	v_mfma_f32_16x16x32_bf16 v[52:55], v[162:165], v[206:209], v[52:55]
	v_mfma_f32_16x16x32_bf16 v[48:51], v[170:173], v[206:209], v[48:51]
	v_mfma_f32_16x16x32_bf16 v[44:47], v[162:165], v[214:217], v[44:47]
	v_mfma_f32_16x16x32_bf16 v[40:43], v[170:173], v[214:217], v[40:43]
	v_mfma_f32_16x16x32_bf16 v[36:39], v[162:165], v[222:225], v[36:39]
	v_mfma_f32_16x16x32_bf16 v[32:35], v[170:173], v[222:225], v[32:35]
	v_mfma_f32_16x16x32_bf16 v[28:31], v[226:229], v[174:177], v[28:31]
	v_mfma_f32_16x16x32_bf16 v[24:27], v[234:237], v[174:177], v[24:27]
	v_mfma_f32_16x16x32_bf16 v[20:23], v[226:229], v[182:185], v[20:23]
	v_mfma_f32_16x16x32_bf16 v[16:19], v[234:237], v[182:185], v[16:19]
	v_mfma_f32_16x16x32_bf16 v[12:15], v[226:229], v[210:213], v[12:15]
	v_mfma_f32_16x16x32_bf16 v[8:11], v[234:237], v[210:213], v[8:11]
	v_mfma_f32_16x16x32_bf16 v[4:7], v[226:229], v[218:221], v[4:7]
	v_mfma_f32_16x16x32_bf16 v[0:3], v[234:237], v[218:221], v[0:3]
	v_mfma_f32_16x16x32_bf16 v[28:31], v[230:233], v[178:181], v[28:31]
	v_mfma_f32_16x16x32_bf16 v[24:27], v[238:241], v[178:181], v[24:27]
	v_mfma_f32_16x16x32_bf16 v[20:23], v[230:233], v[206:209], v[20:23]
	v_mfma_f32_16x16x32_bf16 v[16:19], v[238:241], v[206:209], v[16:19]
	v_mfma_f32_16x16x32_bf16 v[12:15], v[230:233], v[214:217], v[12:15]
	v_mfma_f32_16x16x32_bf16 v[8:11], v[238:241], v[214:217], v[8:11]
	v_mfma_f32_16x16x32_bf16 v[4:7], v[230:233], v[222:225], v[4:7]
	v_mfma_f32_16x16x32_bf16 v[0:3], v[238:241], v[222:225], v[0:3]
	s_barrier
	s_cbranch_scc0 .LBB0_77
	s_mov_b32 s100, 1
	v_lshl_add_u32 v158, s75, 10, v155
	ds_read2_b32 v[146:147], v158 offset1:16
	ds_read2_b32 v[208:209], v158 offset0:32 offset1:48
	ds_read2_b32 v[210:211], v158 offset0:128 offset1:144
	ds_read2_b32 v[212:213], v158 offset0:160 offset1:176
	s_add_u32 s50, s10, 0xffffff00
	s_addc_u32 s51, s11, -1
	s_ashr_i32 s31, s30, 31
	s_lshl_b64 s[10:11], s[30:31], 8
	s_waitcnt lgkmcnt(0)
	v_mul_f32_e32 v184, 0xbfb8aa3b, v146
	v_mul_f32_e32 v206, v146, v146
	v_pk_mul_f32 v[168:169], v[124:125], v[184:185] op_sel_hi:[1,0]
	v_pk_mul_f32 v[170:171], v[126:127], v[184:185] op_sel_hi:[1,0]
	v_pk_mul_f32 v[172:173], v[120:121], v[184:185] op_sel_hi:[1,0]
	v_pk_mul_f32 v[174:175], v[122:123], v[184:185] op_sel_hi:[1,0]
	v_exp_f32_e32 v168, v168
	v_exp_f32_e32 v169, v169
	v_exp_f32_e32 v170, v170
	v_exp_f32_e32 v171, v171
	v_exp_f32_e32 v172, v172
	v_exp_f32_e32 v173, v173
	v_exp_f32_e32 v174, v174
	v_exp_f32_e32 v175, v175
	v_pk_mul_f32 v[176:177], v[124:125], v[92:93]
	v_pk_mul_f32 v[178:179], v[126:127], v[94:95]
	v_pk_mul_f32 v[180:181], v[120:121], v[88:89]
	v_pk_mul_f32 v[182:183], v[122:123], v[90:91]
	v_pk_add_f32 v[168:169], v[168:169], 1.0 op_sel_hi:[1,0]
	v_pk_add_f32 v[170:171], v[170:171], 1.0 op_sel_hi:[1,0]
	v_pk_add_f32 v[172:173], v[172:173], 1.0 op_sel_hi:[1,0]
	v_pk_add_f32 v[174:175], v[174:175], 1.0 op_sel_hi:[1,0]
	v_rcp_f32_e32 v168, v168
	v_rcp_f32_e32 v169, v169
	v_rcp_f32_e32 v170, v170
	v_rcp_f32_e32 v171, v171
	v_rcp_f32_e32 v172, v172
	v_rcp_f32_e32 v173, v173
	v_rcp_f32_e32 v174, v174
	v_rcp_f32_e32 v175, v175
	v_pk_mul_f32 v[176:177], v[176:177], v[206:207] op_sel_hi:[1,0]
	v_pk_mul_f32 v[178:179], v[178:179], v[206:207] op_sel_hi:[1,0]
	v_pk_mul_f32 v[180:181], v[180:181], v[206:207] op_sel_hi:[1,0]
	v_pk_mul_f32 v[182:183], v[182:183], v[206:207] op_sel_hi:[1,0]
	v_pk_mul_f32 v[176:177], v[176:177], v[168:169]
	v_pk_mul_f32 v[178:179], v[178:179], v[170:171]
	v_pk_mul_f32 v[180:181], v[180:181], v[172:173]
	v_pk_mul_f32 v[182:183], v[182:183], v[174:175]
	v_cvt_pk_bf16_f32 v160, v176, v177
	v_cvt_pk_bf16_f32 v161, v178, v179
	v_cvt_pk_bf16_f32 v162, v180, v181
	v_cvt_pk_bf16_f32 v163, v182, v183
	v_lshl_add_u64 v[152:153], v[134:135], 0, s[10:11]
	s_movk_i32 s6, 0x1600
	v_lshl_or_b32 v150, s74, 7, v156
	v_ashrrev_i32_e32 v151, 31, v150
	s_nop 1
	v_mov_b64_e32 v[148:149], s[28:29]
	v_mad_u64_u32 v[148:149], s[10:11], v152, s6, v[148:149]
	v_mov_b32_e32 v146, v149
	v_mad_u64_u32 v[152:153], s[10:11], v153, s6, v[146:147]
	v_mov_b32_e32 v149, v152
	v_mov_b32_e32 v146, v147
	v_lshl_add_u64 v[150:151], v[150:151], 1, v[148:149]
	global_store_dwordx4 v[150:151], v[160:163], off
	v_mul_f32_e32 v184, 0xbfb8aa3b, v146
	v_mul_f32_e32 v206, v146, v146
	v_pk_mul_f32 v[168:169], v[116:117], v[184:185] op_sel_hi:[1,0]
	v_pk_mul_f32 v[170:171], v[118:119], v[184:185] op_sel_hi:[1,0]
	v_pk_mul_f32 v[172:173], v[112:113], v[184:185] op_sel_hi:[1,0]
	v_pk_mul_f32 v[174:175], v[114:115], v[184:185] op_sel_hi:[1,0]
	v_exp_f32_e32 v168, v168
	v_exp_f32_e32 v169, v169
	v_exp_f32_e32 v170, v170
	v_exp_f32_e32 v171, v171
	v_exp_f32_e32 v172, v172
	v_exp_f32_e32 v173, v173
	v_exp_f32_e32 v174, v174
	v_exp_f32_e32 v175, v175
	v_pk_mul_f32 v[176:177], v[116:117], v[84:85]
	v_pk_mul_f32 v[178:179], v[118:119], v[86:87]
	v_pk_mul_f32 v[180:181], v[112:113], v[80:81]
	v_pk_mul_f32 v[182:183], v[114:115], v[82:83]
	v_pk_add_f32 v[168:169], v[168:169], 1.0 op_sel_hi:[1,0]
	v_pk_add_f32 v[170:171], v[170:171], 1.0 op_sel_hi:[1,0]
	v_pk_add_f32 v[172:173], v[172:173], 1.0 op_sel_hi:[1,0]
	v_pk_add_f32 v[174:175], v[174:175], 1.0 op_sel_hi:[1,0]
	v_rcp_f32_e32 v168, v168
	v_rcp_f32_e32 v169, v169
	v_rcp_f32_e32 v170, v170
	v_rcp_f32_e32 v171, v171
	v_rcp_f32_e32 v172, v172
	v_rcp_f32_e32 v173, v173
	v_rcp_f32_e32 v174, v174
	v_rcp_f32_e32 v175, v175
	v_pk_mul_f32 v[176:177], v[176:177], v[206:207] op_sel_hi:[1,0]
	v_pk_mul_f32 v[178:179], v[178:179], v[206:207] op_sel_hi:[1,0]
	v_pk_mul_f32 v[180:181], v[180:181], v[206:207] op_sel_hi:[1,0]
	v_pk_mul_f32 v[182:183], v[182:183], v[206:207] op_sel_hi:[1,0]
	v_pk_mul_f32 v[176:177], v[176:177], v[168:169]
	v_pk_mul_f32 v[178:179], v[178:179], v[170:171]
	v_pk_mul_f32 v[180:181], v[180:181], v[172:173]
	v_pk_mul_f32 v[182:183], v[182:183], v[174:175]
	v_cvt_pk_bf16_f32 v160, v176, v177
	v_cvt_pk_bf16_f32 v161, v178, v179
	v_cvt_pk_bf16_f32 v162, v180, v181
	v_cvt_pk_bf16_f32 v163, v182, v183
	s_mov_b32 s6, 0x16000
	s_mov_b64 s[10:11], 0x16000
	s_nop 1
	v_lshl_add_u64 v[146:147], v[150:151], 0, s[10:11]
	global_store_dwordx4 v[146:147], v[160:163], off
	v_mov_b32_e32 v146, v208
	v_mov_b32_e32 v147, v209
	s_mov_b32 s6, 0x2c000
	s_waitcnt lgkmcnt(0)
	v_mul_f32_e32 v184, 0xbfb8aa3b, v146
	v_mul_f32_e32 v206, v146, v146
	v_pk_mul_f32 v[168:169], v[108:109], v[184:185] op_sel_hi:[1,0]
	v_pk_mul_f32 v[170:171], v[110:111], v[184:185] op_sel_hi:[1,0]
	v_pk_mul_f32 v[172:173], v[104:105], v[184:185] op_sel_hi:[1,0]
	v_pk_mul_f32 v[174:175], v[106:107], v[184:185] op_sel_hi:[1,0]
	v_exp_f32_e32 v168, v168
	v_exp_f32_e32 v169, v169
	v_exp_f32_e32 v170, v170
	v_exp_f32_e32 v171, v171
	v_exp_f32_e32 v172, v172
	v_exp_f32_e32 v173, v173
	v_exp_f32_e32 v174, v174
	v_exp_f32_e32 v175, v175
	v_pk_mul_f32 v[176:177], v[108:109], v[76:77]
	v_pk_mul_f32 v[178:179], v[110:111], v[78:79]
	v_pk_mul_f32 v[180:181], v[104:105], v[72:73]
	v_pk_mul_f32 v[182:183], v[106:107], v[74:75]
	v_pk_add_f32 v[168:169], v[168:169], 1.0 op_sel_hi:[1,0]
	v_pk_add_f32 v[170:171], v[170:171], 1.0 op_sel_hi:[1,0]
	v_pk_add_f32 v[172:173], v[172:173], 1.0 op_sel_hi:[1,0]
	v_pk_add_f32 v[174:175], v[174:175], 1.0 op_sel_hi:[1,0]
	v_rcp_f32_e32 v168, v168
	v_rcp_f32_e32 v169, v169
	v_rcp_f32_e32 v170, v170
	v_rcp_f32_e32 v171, v171
	v_rcp_f32_e32 v172, v172
	v_rcp_f32_e32 v173, v173
	v_rcp_f32_e32 v174, v174
	v_rcp_f32_e32 v175, v175
	v_pk_mul_f32 v[176:177], v[176:177], v[206:207] op_sel_hi:[1,0]
	v_pk_mul_f32 v[178:179], v[178:179], v[206:207] op_sel_hi:[1,0]
	v_pk_mul_f32 v[180:181], v[180:181], v[206:207] op_sel_hi:[1,0]
	v_pk_mul_f32 v[182:183], v[182:183], v[206:207] op_sel_hi:[1,0]
	v_pk_mul_f32 v[176:177], v[176:177], v[168:169]
	v_pk_mul_f32 v[178:179], v[178:179], v[170:171]
	v_pk_mul_f32 v[180:181], v[180:181], v[172:173]
	v_pk_mul_f32 v[182:183], v[182:183], v[174:175]
	v_cvt_pk_bf16_f32 v160, v176, v177
	v_cvt_pk_bf16_f32 v161, v178, v179
	v_cvt_pk_bf16_f32 v162, v180, v181
	v_cvt_pk_bf16_f32 v163, v182, v183
	s_nop 1
	v_mov_b32_e32 v146, v147
	s_mov_b64 s[10:11], 0x2c000
	v_lshl_add_u64 v[148:149], v[150:151], 0, s[10:11]
	global_store_dwordx4 v[148:149], v[160:163], off
	v_mul_f32_e32 v184, 0xbfb8aa3b, v146
	v_mul_f32_e32 v206, v146, v146
	v_pk_mul_f32 v[168:169], v[100:101], v[184:185] op_sel_hi:[1,0]
	v_pk_mul_f32 v[170:171], v[102:103], v[184:185] op_sel_hi:[1,0]
	v_pk_mul_f32 v[172:173], v[96:97], v[184:185] op_sel_hi:[1,0]
	v_pk_mul_f32 v[174:175], v[98:99], v[184:185] op_sel_hi:[1,0]
	v_exp_f32_e32 v168, v168
	v_exp_f32_e32 v169, v169
	v_exp_f32_e32 v170, v170
	v_exp_f32_e32 v171, v171
	v_exp_f32_e32 v172, v172
	v_exp_f32_e32 v173, v173
	v_exp_f32_e32 v174, v174
	v_exp_f32_e32 v175, v175
	v_pk_mul_f32 v[176:177], v[100:101], v[68:69]
	v_pk_mul_f32 v[178:179], v[102:103], v[70:71]
	v_pk_mul_f32 v[180:181], v[96:97], v[64:65]
	v_pk_mul_f32 v[182:183], v[98:99], v[66:67]
	v_pk_add_f32 v[168:169], v[168:169], 1.0 op_sel_hi:[1,0]
	v_pk_add_f32 v[170:171], v[170:171], 1.0 op_sel_hi:[1,0]
	v_pk_add_f32 v[172:173], v[172:173], 1.0 op_sel_hi:[1,0]
	v_pk_add_f32 v[174:175], v[174:175], 1.0 op_sel_hi:[1,0]
	v_rcp_f32_e32 v168, v168
	v_rcp_f32_e32 v169, v169
	v_rcp_f32_e32 v170, v170
	v_rcp_f32_e32 v171, v171
	v_rcp_f32_e32 v172, v172
	v_rcp_f32_e32 v173, v173
	v_rcp_f32_e32 v174, v174
	v_rcp_f32_e32 v175, v175
	v_pk_mul_f32 v[176:177], v[176:177], v[206:207] op_sel_hi:[1,0]
	v_pk_mul_f32 v[178:179], v[178:179], v[206:207] op_sel_hi:[1,0]
	v_pk_mul_f32 v[180:181], v[180:181], v[206:207] op_sel_hi:[1,0]
	v_pk_mul_f32 v[182:183], v[182:183], v[206:207] op_sel_hi:[1,0]
	v_pk_mul_f32 v[176:177], v[176:177], v[168:169]
	v_pk_mul_f32 v[178:179], v[178:179], v[170:171]
	v_pk_mul_f32 v[180:181], v[180:181], v[172:173]
	v_pk_mul_f32 v[182:183], v[182:183], v[174:175]
	v_cvt_pk_bf16_f32 v160, v176, v177
	v_cvt_pk_bf16_f32 v161, v178, v179
	v_cvt_pk_bf16_f32 v162, v180, v181
	v_cvt_pk_bf16_f32 v163, v182, v183
	s_mov_b32 s6, 0x42000
	s_mov_b64 s[10:11], 0x42000
	s_nop 1
	v_lshl_add_u64 v[146:147], v[150:151], 0, s[10:11]
	global_store_dwordx4 v[146:147], v[160:163], off
	v_mov_b32_e32 v146, v210
	v_mov_b32_e32 v147, v211
	s_mov_b32 s6, 0xb0000
	s_waitcnt lgkmcnt(0)
	v_mul_f32_e32 v184, 0xbfb8aa3b, v146
	v_mul_f32_e32 v206, v146, v146
	v_pk_mul_f32 v[168:169], v[60:61], v[184:185] op_sel_hi:[1,0]
	v_pk_mul_f32 v[170:171], v[62:63], v[184:185] op_sel_hi:[1,0]
	v_pk_mul_f32 v[172:173], v[56:57], v[184:185] op_sel_hi:[1,0]
	v_pk_mul_f32 v[174:175], v[58:59], v[184:185] op_sel_hi:[1,0]
	v_exp_f32_e32 v168, v168
	v_exp_f32_e32 v169, v169
	v_exp_f32_e32 v170, v170
	v_exp_f32_e32 v171, v171
	v_exp_f32_e32 v172, v172
	v_exp_f32_e32 v173, v173
	v_exp_f32_e32 v174, v174
	v_exp_f32_e32 v175, v175
	v_pk_mul_f32 v[176:177], v[60:61], v[28:29]
	v_pk_mul_f32 v[178:179], v[62:63], v[30:31]
	v_pk_mul_f32 v[180:181], v[56:57], v[24:25]
	v_pk_mul_f32 v[182:183], v[58:59], v[26:27]
	v_pk_add_f32 v[168:169], v[168:169], 1.0 op_sel_hi:[1,0]
	v_pk_add_f32 v[170:171], v[170:171], 1.0 op_sel_hi:[1,0]
	v_pk_add_f32 v[172:173], v[172:173], 1.0 op_sel_hi:[1,0]
	v_pk_add_f32 v[174:175], v[174:175], 1.0 op_sel_hi:[1,0]
	v_rcp_f32_e32 v168, v168
	v_rcp_f32_e32 v169, v169
	v_rcp_f32_e32 v170, v170
	v_rcp_f32_e32 v171, v171
	v_rcp_f32_e32 v172, v172
	v_rcp_f32_e32 v173, v173
	v_rcp_f32_e32 v174, v174
	v_rcp_f32_e32 v175, v175
	v_pk_mul_f32 v[176:177], v[176:177], v[206:207] op_sel_hi:[1,0]
	v_pk_mul_f32 v[178:179], v[178:179], v[206:207] op_sel_hi:[1,0]
	v_pk_mul_f32 v[180:181], v[180:181], v[206:207] op_sel_hi:[1,0]
	v_pk_mul_f32 v[182:183], v[182:183], v[206:207] op_sel_hi:[1,0]
	v_pk_mul_f32 v[176:177], v[176:177], v[168:169]
	v_pk_mul_f32 v[178:179], v[178:179], v[170:171]
	v_pk_mul_f32 v[180:181], v[180:181], v[172:173]
	v_pk_mul_f32 v[182:183], v[182:183], v[174:175]
	v_cvt_pk_bf16_f32 v160, v176, v177
	v_cvt_pk_bf16_f32 v161, v178, v179
	v_cvt_pk_bf16_f32 v162, v180, v181
	v_cvt_pk_bf16_f32 v163, v182, v183
	s_nop 1
	v_mov_b32_e32 v146, v147
	s_mov_b64 s[10:11], 0xb0000
	v_lshl_add_u64 v[148:149], v[150:151], 0, s[10:11]
	global_store_dwordx4 v[148:149], v[160:163], off
	v_mul_f32_e32 v184, 0xbfb8aa3b, v146
	v_mul_f32_e32 v206, v146, v146
	v_pk_mul_f32 v[168:169], v[52:53], v[184:185] op_sel_hi:[1,0]
	v_pk_mul_f32 v[170:171], v[54:55], v[184:185] op_sel_hi:[1,0]
	v_pk_mul_f32 v[172:173], v[48:49], v[184:185] op_sel_hi:[1,0]
	v_pk_mul_f32 v[174:175], v[50:51], v[184:185] op_sel_hi:[1,0]
	v_exp_f32_e32 v168, v168
	v_exp_f32_e32 v169, v169
	v_exp_f32_e32 v170, v170
	v_exp_f32_e32 v171, v171
	v_exp_f32_e32 v172, v172
	v_exp_f32_e32 v173, v173
	v_exp_f32_e32 v174, v174
	v_exp_f32_e32 v175, v175
	v_pk_mul_f32 v[176:177], v[52:53], v[20:21]
	v_pk_mul_f32 v[178:179], v[54:55], v[22:23]
	v_pk_mul_f32 v[180:181], v[48:49], v[16:17]
	v_pk_mul_f32 v[182:183], v[50:51], v[18:19]
	v_pk_add_f32 v[168:169], v[168:169], 1.0 op_sel_hi:[1,0]
	v_pk_add_f32 v[170:171], v[170:171], 1.0 op_sel_hi:[1,0]
	v_pk_add_f32 v[172:173], v[172:173], 1.0 op_sel_hi:[1,0]
	v_pk_add_f32 v[174:175], v[174:175], 1.0 op_sel_hi:[1,0]
	v_rcp_f32_e32 v168, v168
	v_rcp_f32_e32 v169, v169
	v_rcp_f32_e32 v170, v170
	v_rcp_f32_e32 v171, v171
	v_rcp_f32_e32 v172, v172
	v_rcp_f32_e32 v173, v173
	v_rcp_f32_e32 v174, v174
	v_rcp_f32_e32 v175, v175
	v_pk_mul_f32 v[176:177], v[176:177], v[206:207] op_sel_hi:[1,0]
	v_pk_mul_f32 v[178:179], v[178:179], v[206:207] op_sel_hi:[1,0]
	v_pk_mul_f32 v[180:181], v[180:181], v[206:207] op_sel_hi:[1,0]
	v_pk_mul_f32 v[182:183], v[182:183], v[206:207] op_sel_hi:[1,0]
	v_pk_mul_f32 v[176:177], v[176:177], v[168:169]
	v_pk_mul_f32 v[178:179], v[178:179], v[170:171]
	v_pk_mul_f32 v[180:181], v[180:181], v[172:173]
	v_pk_mul_f32 v[182:183], v[182:183], v[174:175]
	v_cvt_pk_bf16_f32 v160, v176, v177
	v_cvt_pk_bf16_f32 v161, v178, v179
	v_cvt_pk_bf16_f32 v162, v180, v181
	v_cvt_pk_bf16_f32 v163, v182, v183
	s_mov_b32 s6, 0xc6000
	s_mov_b64 s[10:11], 0xc6000
	s_nop 1
	v_lshl_add_u64 v[146:147], v[150:151], 0, s[10:11]
	global_store_dwordx4 v[146:147], v[160:163], off
	v_mov_b32_e32 v146, v212
	v_mov_b32_e32 v147, v213
	s_mov_b32 s6, 0xdc000
	s_waitcnt lgkmcnt(0)
	v_mul_f32_e32 v184, 0xbfb8aa3b, v146
	v_mul_f32_e32 v206, v146, v146
	v_pk_mul_f32 v[168:169], v[44:45], v[184:185] op_sel_hi:[1,0]
	v_pk_mul_f32 v[170:171], v[46:47], v[184:185] op_sel_hi:[1,0]
	v_pk_mul_f32 v[172:173], v[40:41], v[184:185] op_sel_hi:[1,0]
	v_pk_mul_f32 v[174:175], v[42:43], v[184:185] op_sel_hi:[1,0]
	v_exp_f32_e32 v168, v168
	v_exp_f32_e32 v169, v169
	v_exp_f32_e32 v170, v170
	v_exp_f32_e32 v171, v171
	v_exp_f32_e32 v172, v172
	v_exp_f32_e32 v173, v173
	v_exp_f32_e32 v174, v174
	v_exp_f32_e32 v175, v175
	v_pk_mul_f32 v[176:177], v[44:45], v[12:13]
	v_pk_mul_f32 v[178:179], v[46:47], v[14:15]
	v_pk_mul_f32 v[180:181], v[40:41], v[8:9]
	v_pk_mul_f32 v[182:183], v[42:43], v[10:11]
	v_pk_add_f32 v[168:169], v[168:169], 1.0 op_sel_hi:[1,0]
	v_pk_add_f32 v[170:171], v[170:171], 1.0 op_sel_hi:[1,0]
	v_pk_add_f32 v[172:173], v[172:173], 1.0 op_sel_hi:[1,0]
	v_pk_add_f32 v[174:175], v[174:175], 1.0 op_sel_hi:[1,0]
	v_rcp_f32_e32 v168, v168
	v_rcp_f32_e32 v169, v169
	v_rcp_f32_e32 v170, v170
	v_rcp_f32_e32 v171, v171
	v_rcp_f32_e32 v172, v172
	v_rcp_f32_e32 v173, v173
	v_rcp_f32_e32 v174, v174
	v_rcp_f32_e32 v175, v175
	v_pk_mul_f32 v[176:177], v[176:177], v[206:207] op_sel_hi:[1,0]
	v_pk_mul_f32 v[178:179], v[178:179], v[206:207] op_sel_hi:[1,0]
	v_pk_mul_f32 v[180:181], v[180:181], v[206:207] op_sel_hi:[1,0]
	v_pk_mul_f32 v[182:183], v[182:183], v[206:207] op_sel_hi:[1,0]
	v_pk_mul_f32 v[176:177], v[176:177], v[168:169]
	v_pk_mul_f32 v[178:179], v[178:179], v[170:171]
	v_pk_mul_f32 v[180:181], v[180:181], v[172:173]
	v_pk_mul_f32 v[182:183], v[182:183], v[174:175]
	v_cvt_pk_bf16_f32 v158, v176, v177
	v_cvt_pk_bf16_f32 v159, v178, v179
	v_cvt_pk_bf16_f32 v160, v180, v181
	v_cvt_pk_bf16_f32 v161, v182, v183
	s_nop 1
	v_mov_b32_e32 v146, v147
	s_mov_b64 s[10:11], 0xdc000
	v_lshl_add_u64 v[148:149], v[150:151], 0, s[10:11]
	global_store_dwordx4 v[148:149], v[158:161], off
	v_mul_f32_e32 v184, 0xbfb8aa3b, v146
	v_mul_f32_e32 v206, v146, v146
	v_pk_mul_f32 v[168:169], v[36:37], v[184:185] op_sel_hi:[1,0]
	v_pk_mul_f32 v[170:171], v[38:39], v[184:185] op_sel_hi:[1,0]
	v_pk_mul_f32 v[172:173], v[32:33], v[184:185] op_sel_hi:[1,0]
	v_pk_mul_f32 v[174:175], v[34:35], v[184:185] op_sel_hi:[1,0]
	v_exp_f32_e32 v168, v168
	v_exp_f32_e32 v169, v169
	v_exp_f32_e32 v170, v170
	v_exp_f32_e32 v171, v171
	v_exp_f32_e32 v172, v172
	v_exp_f32_e32 v173, v173
	v_exp_f32_e32 v174, v174
	v_exp_f32_e32 v175, v175
	v_pk_mul_f32 v[176:177], v[36:37], v[4:5]
	v_pk_mul_f32 v[178:179], v[38:39], v[6:7]
	v_pk_mul_f32 v[180:181], v[32:33], v[0:1]
	v_pk_mul_f32 v[182:183], v[34:35], v[2:3]
	v_pk_add_f32 v[168:169], v[168:169], 1.0 op_sel_hi:[1,0]
	v_pk_add_f32 v[170:171], v[170:171], 1.0 op_sel_hi:[1,0]
	v_pk_add_f32 v[172:173], v[172:173], 1.0 op_sel_hi:[1,0]
	v_pk_add_f32 v[174:175], v[174:175], 1.0 op_sel_hi:[1,0]
	v_rcp_f32_e32 v168, v168
	v_rcp_f32_e32 v169, v169
	v_rcp_f32_e32 v170, v170
	v_rcp_f32_e32 v171, v171
	v_rcp_f32_e32 v172, v172
	v_rcp_f32_e32 v173, v173
	v_rcp_f32_e32 v174, v174
	v_rcp_f32_e32 v175, v175
	v_pk_mul_f32 v[176:177], v[176:177], v[206:207] op_sel_hi:[1,0]
	v_pk_mul_f32 v[178:179], v[178:179], v[206:207] op_sel_hi:[1,0]
	v_pk_mul_f32 v[180:181], v[180:181], v[206:207] op_sel_hi:[1,0]
	v_pk_mul_f32 v[182:183], v[182:183], v[206:207] op_sel_hi:[1,0]
	v_pk_mul_f32 v[176:177], v[176:177], v[168:169]
	v_pk_mul_f32 v[178:179], v[178:179], v[170:171]
	v_pk_mul_f32 v[180:181], v[180:181], v[172:173]
	v_pk_mul_f32 v[182:183], v[182:183], v[174:175]
	v_cvt_pk_bf16_f32 v158, v176, v177
	v_cvt_pk_bf16_f32 v159, v178, v179
	v_cvt_pk_bf16_f32 v160, v180, v181
	v_cvt_pk_bf16_f32 v161, v182, v183
	s_mov_b64 s[10:11], 0xf2000
	s_nop 1
	v_lshl_add_u64 v[146:147], v[150:151], 0, s[10:11]
	s_andn2_b64 vcc, exec, s[44:45]
	global_store_dwordx4 v[146:147], v[158:161], off
	s_cbranch_vccz .LBB0_73
	s_mov_b64 s[46:47], s[50:51]
	s_andn2_b64 vcc, exec, s[42:43]
	s_mov_b64 s[50:51], s[46:47]
	s_cbranch_vccnz .LBB0_74

.LBB0_386:
	s_add_u32 s6, s28, s52
	s_addc_u32 s19, s29, s53
	s_add_u32 s6, s6, 0x100
	s_addc_u32 s19, s19, 0
	s_add_u32 s23, s10, s52
	s_addc_u32 s54, s11, s53
	s_add_i32 s82, 0, 0x10000
	v_add_u32_e32 v146, s82, v154
	ds_read_b128 v[158:161], v146
	ds_read_b128 v[162:165], v146 offset:1024
	ds_read_b128 v[166:169], v146 offset:2048
	ds_read_b128 v[170:173], v146 offset:3072
	s_cmpk_eq_i32 s52, 0x700
	s_cselect_b32 s59, s12, s19
	s_cselect_b32 s58, s35, s6
	s_cselect_b32 s55, s39, s54
	s_cselect_b32 s54, s47, s23
	v_lshl_add_u64 v[146:147], v[150:151], 0, s[52:53]
	s_add_i32 m0, s68, 0xc000
	ds_read_b128 v[174:177], v157
	ds_read_b128 v[178:181], v157 offset:1024
	ds_read_b128 v[182:185], v157 offset:2048
	ds_read_b128 v[206:209], v157 offset:3072
	ds_read_b128 v[210:213], v157 offset:4096
	ds_read_b128 v[214:217], v157 offset:5120
	ds_read_b128 v[218:221], v157 offset:6144
	ds_read_b128 v[222:225], v157 offset:7168
	global_load_lds_dwordx4 v[146:147], off
	v_lshl_add_u64 v[146:147], v[152:153], 0, s[52:53]
	s_add_i32 m0, s68, 0xe000
	s_nop 0
	global_load_lds_dwordx4 v[146:147], off
	s_add_i32 s6, 0, 0x14000
	v_add_u32_e32 v146, s6, v154
	ds_read_b128 v[226:229], v146
	ds_read_b128 v[230:233], v146 offset:1024
	ds_read_b128 v[234:237], v146 offset:2048
	ds_read_b128 v[238:241], v146 offset:3072
	s_nop 0
	s_waitcnt vmcnt(8)
	s_waitcnt lgkmcnt(0)
	s_barrier
	v_mfma_f32_16x16x32_bf16 v[124:127], v[158:161], v[174:177], v[124:127]
	v_mfma_f32_16x16x32_bf16 v[120:123], v[166:169], v[174:177], v[120:123]
	v_mfma_f32_16x16x32_bf16 v[116:119], v[158:161], v[182:185], v[116:119]
	v_mfma_f32_16x16x32_bf16 v[112:115], v[166:169], v[182:185], v[112:115]
	v_mfma_f32_16x16x32_bf16 v[108:111], v[158:161], v[210:213], v[108:111]
	v_mfma_f32_16x16x32_bf16 v[104:107], v[166:169], v[210:213], v[104:107]
	v_mfma_f32_16x16x32_bf16 v[100:103], v[158:161], v[218:221], v[100:103]
	v_mfma_f32_16x16x32_bf16 v[96:99], v[166:169], v[218:221], v[96:99]
	v_mfma_f32_16x16x32_bf16 v[124:127], v[162:165], v[178:181], v[124:127]
	v_mfma_f32_16x16x32_bf16 v[120:123], v[170:173], v[178:181], v[120:123]
	v_mfma_f32_16x16x32_bf16 v[116:119], v[162:165], v[206:209], v[116:119]
	v_mfma_f32_16x16x32_bf16 v[112:115], v[170:173], v[206:209], v[112:115]
	v_mfma_f32_16x16x32_bf16 v[108:111], v[162:165], v[214:217], v[108:111]
	v_mfma_f32_16x16x32_bf16 v[104:107], v[170:173], v[214:217], v[104:107]
	v_mfma_f32_16x16x32_bf16 v[100:103], v[162:165], v[222:225], v[100:103]
	v_mfma_f32_16x16x32_bf16 v[96:99], v[170:173], v[222:225], v[96:99]
	v_mfma_f32_16x16x32_bf16 v[92:95], v[226:229], v[174:177], v[92:95]
	v_mfma_f32_16x16x32_bf16 v[88:91], v[234:237], v[174:177], v[88:91]
	v_mfma_f32_16x16x32_bf16 v[84:87], v[226:229], v[182:185], v[84:87]
	v_mfma_f32_16x16x32_bf16 v[80:83], v[234:237], v[182:185], v[80:83]
	v_mfma_f32_16x16x32_bf16 v[76:79], v[226:229], v[210:213], v[76:79]
	v_mfma_f32_16x16x32_bf16 v[72:75], v[234:237], v[210:213], v[72:75]
	v_mfma_f32_16x16x32_bf16 v[68:71], v[226:229], v[218:221], v[68:71]
	v_mfma_f32_16x16x32_bf16 v[64:67], v[234:237], v[218:221], v[64:67]
	v_mfma_f32_16x16x32_bf16 v[92:95], v[230:233], v[178:181], v[92:95]
	v_mfma_f32_16x16x32_bf16 v[88:91], v[238:241], v[178:181], v[88:91]
	v_mfma_f32_16x16x32_bf16 v[84:87], v[230:233], v[206:209], v[84:87]
	v_mfma_f32_16x16x32_bf16 v[80:83], v[238:241], v[206:209], v[80:83]
	v_mfma_f32_16x16x32_bf16 v[76:79], v[230:233], v[214:217], v[76:79]
	v_mfma_f32_16x16x32_bf16 v[72:75], v[238:241], v[214:217], v[72:75]
	v_mfma_f32_16x16x32_bf16 v[68:71], v[230:233], v[222:225], v[68:71]
	v_mfma_f32_16x16x32_bf16 v[64:67], v[238:241], v[222:225], v[64:67]
	s_barrier
	s_add_i32 s19, s82, s57
	v_lshl_add_u64 v[146:147], s[54:55], 0, v[140:141]
	s_mov_b32 m0, s19
	v_lshl_add_u64 v[148:149], s[54:55], 0, v[132:133]
	global_load_lds_dwordx4 v[146:147], off
	s_add_i32 m0, s19, 0x2000
	s_nop 0
	global_load_lds_dwordx4 v[148:149], off
	s_mov_b32 m0, s68
	v_lshl_add_u64 v[194:195], s[58:59], 0, v[128:129]
	ds_read_b128 v[174:177], v157 offset:16384
	ds_read_b128 v[178:181], v157 offset:17408
	ds_read_b128 v[182:185], v157 offset:18432
	ds_read_b128 v[206:209], v157 offset:19456
	ds_read_b128 v[210:213], v157 offset:20480
	ds_read_b128 v[214:217], v157 offset:21504
	ds_read_b128 v[218:221], v157 offset:22528
	ds_read_b128 v[222:225], v157 offset:23552
	global_load_lds_dwordx4 v[194:195], off
	v_lshl_add_u64 v[196:197], s[58:59], 0, v[130:131]
	s_mov_b32 m0, s69
	s_nop 0
	global_load_lds_dwordx4 v[196:197], off
	s_add_u32 s82, s54, 0x40000
	s_addc_u32 s83, s55, 0
	s_add_i32 s6, s6, s57
	v_lshl_add_u64 v[250:251], s[82:83], 0, v[140:141]
	s_mov_b32 m0, s6
	s_nop 0
	global_load_lds_dwordx4 v[250:251], off
	v_lshl_add_u64 v[250:251], s[82:83], 0, v[132:133]
	s_add_i32 m0, s6, 0x2000
	s_nop 0
	global_load_lds_dwordx4 v[250:251], off
	s_nop 0
	s_waitcnt vmcnt(8)
	s_waitcnt lgkmcnt(0)
	s_barrier
	v_mfma_f32_16x16x32_bf16 v[60:63], v[158:161], v[174:177], v[60:63]
	v_mfma_f32_16x16x32_bf16 v[56:59], v[166:169], v[174:177], v[56:59]
	v_mfma_f32_16x16x32_bf16 v[52:55], v[158:161], v[182:185], v[52:55]
	v_mfma_f32_16x16x32_bf16 v[48:51], v[166:169], v[182:185], v[48:51]
	v_mfma_f32_16x16x32_bf16 v[44:47], v[158:161], v[210:213], v[44:47]
	v_mfma_f32_16x16x32_bf16 v[40:43], v[166:169], v[210:213], v[40:43]
	v_mfma_f32_16x16x32_bf16 v[36:39], v[158:161], v[218:221], v[36:39]
	v_mfma_f32_16x16x32_bf16 v[32:35], v[166:169], v[218:221], v[32:35]
	v_mfma_f32_16x16x32_bf16 v[60:63], v[162:165], v[178:181], v[60:63]
	v_mfma_f32_16x16x32_bf16 v[56:59], v[170:173], v[178:181], v[56:59]
	v_mfma_f32_16x16x32_bf16 v[52:55], v[162:165], v[206:209], v[52:55]
	v_mfma_f32_16x16x32_bf16 v[48:51], v[170:173], v[206:209], v[48:51]
	v_mfma_f32_16x16x32_bf16 v[44:47], v[162:165], v[214:217], v[44:47]
	v_mfma_f32_16x16x32_bf16 v[40:43], v[170:173], v[214:217], v[40:43]
	v_mfma_f32_16x16x32_bf16 v[36:39], v[162:165], v[222:225], v[36:39]
	v_mfma_f32_16x16x32_bf16 v[32:35], v[170:173], v[222:225], v[32:35]
	v_mfma_f32_16x16x32_bf16 v[28:31], v[226:229], v[174:177], v[28:31]
	v_mfma_f32_16x16x32_bf16 v[24:27], v[234:237], v[174:177], v[24:27]
	v_mfma_f32_16x16x32_bf16 v[20:23], v[226:229], v[182:185], v[20:23]
	v_mfma_f32_16x16x32_bf16 v[16:19], v[234:237], v[182:185], v[16:19]
	v_mfma_f32_16x16x32_bf16 v[12:15], v[226:229], v[210:213], v[12:15]
	v_mfma_f32_16x16x32_bf16 v[8:11], v[234:237], v[210:213], v[8:11]
	v_mfma_f32_16x16x32_bf16 v[4:7], v[226:229], v[218:221], v[4:7]
	v_mfma_f32_16x16x32_bf16 v[0:3], v[234:237], v[218:221], v[0:3]
	v_mfma_f32_16x16x32_bf16 v[28:31], v[230:233], v[178:181], v[28:31]
	v_mfma_f32_16x16x32_bf16 v[24:27], v[238:241], v[178:181], v[24:27]
	v_mfma_f32_16x16x32_bf16 v[20:23], v[230:233], v[206:209], v[20:23]
	v_mfma_f32_16x16x32_bf16 v[16:19], v[238:241], v[206:209], v[16:19]
	v_mfma_f32_16x16x32_bf16 v[12:15], v[230:233], v[214:217], v[12:15]
	v_mfma_f32_16x16x32_bf16 v[8:11], v[238:241], v[214:217], v[8:11]
	v_mfma_f32_16x16x32_bf16 v[4:7], v[230:233], v[222:225], v[4:7]
	v_mfma_f32_16x16x32_bf16 v[0:3], v[238:241], v[222:225], v[0:3]
	s_barrier
	s_add_i32 s6, 0, 0x18000
	v_add_u32_e32 v170, s6, v154
	ds_read_b128 v[158:161], v170
	ds_read_b128 v[162:165], v170 offset:1024
	ds_read_b128 v[166:169], v170 offset:2048
	ds_read_b128 v[170:173], v170 offset:3072
	s_add_u32 s58, s58, 0x40000
	s_addc_u32 s59, s59, 0
	s_mov_b32 m0, s70
	v_lshl_add_u64 v[226:227], s[58:59], 0, v[128:129]
	ds_read_b128 v[174:177], v157 offset:32768
	ds_read_b128 v[178:181], v157 offset:33792
	ds_read_b128 v[182:185], v157 offset:34816
	ds_read_b128 v[206:209], v157 offset:35840
	ds_read_b128 v[210:213], v157 offset:36864
	ds_read_b128 v[214:217], v157 offset:37888
	ds_read_b128 v[218:221], v157 offset:38912
	ds_read_b128 v[222:225], v157 offset:39936
	global_load_lds_dwordx4 v[226:227], off
	v_lshl_add_u64 v[226:227], s[58:59], 0, v[130:131]
	s_mov_b32 m0, s71
	s_nop 0
	global_load_lds_dwordx4 v[226:227], off
	s_add_i32 s19, 0, 0x1c000
	v_add_u32_e32 v192, s19, v154
	ds_read_b128 v[226:229], v192
	ds_read_b128 v[230:233], v192 offset:1024
	ds_read_b128 v[234:237], v192 offset:2048
	ds_read_b128 v[238:241], v192 offset:3072
	s_waitcnt vmcnt(8)
	s_waitcnt lgkmcnt(0)
	s_barrier
	v_mfma_f32_16x16x32_bf16 v[124:127], v[158:161], v[174:177], v[124:127]
	v_mfma_f32_16x16x32_bf16 v[120:123], v[166:169], v[174:177], v[120:123]
	v_mfma_f32_16x16x32_bf16 v[116:119], v[158:161], v[182:185], v[116:119]
	v_mfma_f32_16x16x32_bf16 v[112:115], v[166:169], v[182:185], v[112:115]
	v_mfma_f32_16x16x32_bf16 v[108:111], v[158:161], v[210:213], v[108:111]
	v_mfma_f32_16x16x32_bf16 v[104:107], v[166:169], v[210:213], v[104:107]
	v_mfma_f32_16x16x32_bf16 v[100:103], v[158:161], v[218:221], v[100:103]
	v_mfma_f32_16x16x32_bf16 v[96:99], v[166:169], v[218:221], v[96:99]
	v_mfma_f32_16x16x32_bf16 v[124:127], v[162:165], v[178:181], v[124:127]
	v_mfma_f32_16x16x32_bf16 v[120:123], v[170:173], v[178:181], v[120:123]
	v_mfma_f32_16x16x32_bf16 v[116:119], v[162:165], v[206:209], v[116:119]
	v_mfma_f32_16x16x32_bf16 v[112:115], v[170:173], v[206:209], v[112:115]
	v_mfma_f32_16x16x32_bf16 v[108:111], v[162:165], v[214:217], v[108:111]
	v_mfma_f32_16x16x32_bf16 v[104:107], v[170:173], v[214:217], v[104:107]
	v_mfma_f32_16x16x32_bf16 v[100:103], v[162:165], v[222:225], v[100:103]
	v_mfma_f32_16x16x32_bf16 v[96:99], v[170:173], v[222:225], v[96:99]
	v_mfma_f32_16x16x32_bf16 v[92:95], v[226:229], v[174:177], v[92:95]
	v_mfma_f32_16x16x32_bf16 v[88:91], v[234:237], v[174:177], v[88:91]
	v_mfma_f32_16x16x32_bf16 v[84:87], v[226:229], v[182:185], v[84:87]
	v_mfma_f32_16x16x32_bf16 v[80:83], v[234:237], v[182:185], v[80:83]
	v_mfma_f32_16x16x32_bf16 v[76:79], v[226:229], v[210:213], v[76:79]
	v_mfma_f32_16x16x32_bf16 v[72:75], v[234:237], v[210:213], v[72:75]
	v_mfma_f32_16x16x32_bf16 v[68:71], v[226:229], v[218:221], v[68:71]
	v_mfma_f32_16x16x32_bf16 v[64:67], v[234:237], v[218:221], v[64:67]
	v_mfma_f32_16x16x32_bf16 v[92:95], v[230:233], v[178:181], v[92:95]
	v_mfma_f32_16x16x32_bf16 v[88:91], v[238:241], v[178:181], v[88:91]
	v_mfma_f32_16x16x32_bf16 v[84:87], v[230:233], v[206:209], v[84:87]
	v_mfma_f32_16x16x32_bf16 v[80:83], v[238:241], v[206:209], v[80:83]
	v_mfma_f32_16x16x32_bf16 v[76:79], v[230:233], v[214:217], v[76:79]
	v_mfma_f32_16x16x32_bf16 v[72:75], v[238:241], v[214:217], v[72:75]
	v_mfma_f32_16x16x32_bf16 v[68:71], v[230:233], v[222:225], v[68:71]
	v_mfma_f32_16x16x32_bf16 v[64:67], v[238:241], v[222:225], v[64:67]
	s_barrier
	s_add_i32 s6, s6, s57
	v_lshl_add_u64 v[146:147], v[146:147], 0, s[36:37]
	s_mov_b32 m0, s6
	s_nop 0
	global_load_lds_dwordx4 v[146:147], off
	v_lshl_add_u64 v[146:147], v[148:149], 0, s[36:37]
	s_add_i32 m0, s6, 0x2000
	s_nop 0
	global_load_lds_dwordx4 v[146:147], off
	s_mov_b32 m0, s72
	v_lshl_add_u64 v[146:147], v[194:195], 0, s[36:37]
	ds_read_b128 v[174:177], v157 offset:49152
	ds_read_b128 v[178:181], v157 offset:50176
	ds_read_b128 v[182:185], v157 offset:51200
	ds_read_b128 v[206:209], v157 offset:52224
	ds_read_b128 v[210:213], v157 offset:53248
	ds_read_b128 v[214:217], v157 offset:54272
	ds_read_b128 v[218:221], v157 offset:55296
	ds_read_b128 v[222:225], v157 offset:56320
	global_load_lds_dwordx4 v[146:147], off
	v_lshl_add_u64 v[146:147], v[196:197], 0, s[36:37]
	s_mov_b32 m0, s73
	s_nop 0
	global_load_lds_dwordx4 v[146:147], off
	s_add_u32 s54, s54, 0x40080
	s_addc_u32 s55, s55, 0
	s_add_i32 s6, s19, s57
	v_lshl_add_u64 v[146:147], s[54:55], 0, v[140:141]
	s_mov_b32 m0, s6
	s_nop 0
	global_load_lds_dwordx4 v[146:147], off
	v_lshl_add_u64 v[146:147], s[54:55], 0, v[132:133]
	s_add_i32 m0, s6, 0x2000
	s_nop 0
	global_load_lds_dwordx4 v[146:147], off
	s_add_i32 s81, s81, 2
	s_add_u32 s52, s52, 0x100
	s_addc_u32 s53, s53, 0
	s_cmp_gt_u32 s81, 13
	s_nop 0
	s_waitcnt vmcnt(8)
	s_waitcnt lgkmcnt(0)
	s_barrier
	v_mfma_f32_16x16x32_bf16 v[60:63], v[158:161], v[174:177], v[60:63]
	v_mfma_f32_16x16x32_bf16 v[56:59], v[166:169], v[174:177], v[56:59]
	v_mfma_f32_16x16x32_bf16 v[52:55], v[158:161], v[182:185], v[52:55]
	v_mfma_f32_16x16x32_bf16 v[48:51], v[166:169], v[182:185], v[48:51]
	v_mfma_f32_16x16x32_bf16 v[44:47], v[158:161], v[210:213], v[44:47]
	v_mfma_f32_16x16x32_bf16 v[40:43], v[166:169], v[210:213], v[40:43]
	v_mfma_f32_16x16x32_bf16 v[36:39], v[158:161], v[218:221], v[36:39]
	v_mfma_f32_16x16x32_bf16 v[32:35], v[166:169], v[218:221], v[32:35]
	v_mfma_f32_16x16x32_bf16 v[60:63], v[162:165], v[178:181], v[60:63]
	v_mfma_f32_16x16x32_bf16 v[56:59], v[170:173], v[178:181], v[56:59]
	v_mfma_f32_16x16x32_bf16 v[52:55], v[162:165], v[206:209], v[52:55]
	v_mfma_f32_16x16x32_bf16 v[48:51], v[170:173], v[206:209], v[48:51]
	v_mfma_f32_16x16x32_bf16 v[44:47], v[162:165], v[214:217], v[44:47]
	v_mfma_f32_16x16x32_bf16 v[40:43], v[170:173], v[214:217], v[40:43]
	v_mfma_f32_16x16x32_bf16 v[36:39], v[162:165], v[222:225], v[36:39]
	v_mfma_f32_16x16x32_bf16 v[32:35], v[170:173], v[222:225], v[32:35]
	v_mfma_f32_16x16x32_bf16 v[28:31], v[226:229], v[174:177], v[28:31]
	v_mfma_f32_16x16x32_bf16 v[24:27], v[234:237], v[174:177], v[24:27]
	v_mfma_f32_16x16x32_bf16 v[20:23], v[226:229], v[182:185], v[20:23]
	v_mfma_f32_16x16x32_bf16 v[16:19], v[234:237], v[182:185], v[16:19]
	v_mfma_f32_16x16x32_bf16 v[12:15], v[226:229], v[210:213], v[12:15]
	v_mfma_f32_16x16x32_bf16 v[8:11], v[234:237], v[210:213], v[8:11]
	v_mfma_f32_16x16x32_bf16 v[4:7], v[226:229], v[218:221], v[4:7]
	v_mfma_f32_16x16x32_bf16 v[0:3], v[234:237], v[218:221], v[0:3]
	v_mfma_f32_16x16x32_bf16 v[28:31], v[230:233], v[178:181], v[28:31]
	v_mfma_f32_16x16x32_bf16 v[24:27], v[238:241], v[178:181], v[24:27]
	v_mfma_f32_16x16x32_bf16 v[20:23], v[230:233], v[206:209], v[20:23]
	v_mfma_f32_16x16x32_bf16 v[16:19], v[238:241], v[206:209], v[16:19]
	v_mfma_f32_16x16x32_bf16 v[12:15], v[230:233], v[214:217], v[12:15]
	v_mfma_f32_16x16x32_bf16 v[8:11], v[238:241], v[214:217], v[8:11]
	v_mfma_f32_16x16x32_bf16 v[4:7], v[230:233], v[222:225], v[4:7]
	v_mfma_f32_16x16x32_bf16 v[0:3], v[238:241], v[222:225], v[0:3]
	s_barrier
	s_cbranch_scc0 .LBB0_386
	s_mov_b32 s100, 1
	v_lshl_add_u32 v158, s75, 10, v155
	ds_read2_b32 v[146:147], v158 offset1:16
	ds_read2_b32 v[208:209], v158 offset0:32 offset1:48
	ds_read2_b32 v[210:211], v158 offset0:128 offset1:144
	ds_read2_b32 v[212:213], v158 offset0:160 offset1:176
	s_add_u32 s52, s10, 0xffffff00
	s_addc_u32 s53, s11, -1
	s_ashr_i32 s35, s34, 31
	s_lshl_b64 s[10:11], s[34:35], 8
	s_waitcnt lgkmcnt(0)
	v_mul_f32_e32 v184, 0xbfb8aa3b, v146
	v_mul_f32_e32 v206, v146, v146
	v_pk_mul_f32 v[168:169], v[124:125], v[184:185] op_sel_hi:[1,0]
	v_pk_mul_f32 v[170:171], v[126:127], v[184:185] op_sel_hi:[1,0]
	v_pk_mul_f32 v[172:173], v[120:121], v[184:185] op_sel_hi:[1,0]
	v_pk_mul_f32 v[174:175], v[122:123], v[184:185] op_sel_hi:[1,0]
	v_exp_f32_e32 v168, v168
	v_exp_f32_e32 v169, v169
	v_exp_f32_e32 v170, v170
	v_exp_f32_e32 v171, v171
	v_exp_f32_e32 v172, v172
	v_exp_f32_e32 v173, v173
	v_exp_f32_e32 v174, v174
	v_exp_f32_e32 v175, v175
	v_pk_mul_f32 v[176:177], v[124:125], v[92:93]
	v_pk_mul_f32 v[178:179], v[126:127], v[94:95]
	v_pk_mul_f32 v[180:181], v[120:121], v[88:89]
	v_pk_mul_f32 v[182:183], v[122:123], v[90:91]
	v_pk_add_f32 v[168:169], v[168:169], 1.0 op_sel_hi:[1,0]
	v_pk_add_f32 v[170:171], v[170:171], 1.0 op_sel_hi:[1,0]
	v_pk_add_f32 v[172:173], v[172:173], 1.0 op_sel_hi:[1,0]
	v_pk_add_f32 v[174:175], v[174:175], 1.0 op_sel_hi:[1,0]
	v_rcp_f32_e32 v168, v168
	v_rcp_f32_e32 v169, v169
	v_rcp_f32_e32 v170, v170
	v_rcp_f32_e32 v171, v171
	v_rcp_f32_e32 v172, v172
	v_rcp_f32_e32 v173, v173
	v_rcp_f32_e32 v174, v174
	v_rcp_f32_e32 v175, v175
	v_pk_mul_f32 v[176:177], v[176:177], v[206:207] op_sel_hi:[1,0]
	v_pk_mul_f32 v[178:179], v[178:179], v[206:207] op_sel_hi:[1,0]
	v_pk_mul_f32 v[180:181], v[180:181], v[206:207] op_sel_hi:[1,0]
	v_pk_mul_f32 v[182:183], v[182:183], v[206:207] op_sel_hi:[1,0]
	v_pk_mul_f32 v[176:177], v[176:177], v[168:169]
	v_pk_mul_f32 v[178:179], v[178:179], v[170:171]
	v_pk_mul_f32 v[180:181], v[180:181], v[172:173]
	v_pk_mul_f32 v[182:183], v[182:183], v[174:175]
	v_cvt_pk_bf16_f32 v160, v176, v177
	v_cvt_pk_bf16_f32 v161, v178, v179
	v_cvt_pk_bf16_f32 v162, v180, v181
	v_cvt_pk_bf16_f32 v163, v182, v183
	v_lshl_add_u64 v[152:153], v[134:135], 0, s[10:11]
	s_movk_i32 s6, 0x1600
	v_lshl_or_b32 v150, s74, 7, v156
	v_ashrrev_i32_e32 v151, 31, v150
	s_nop 1
	v_mov_b64_e32 v[148:149], s[30:31]
	v_mad_u64_u32 v[148:149], s[10:11], v152, s6, v[148:149]
	v_mov_b32_e32 v146, v149
	v_mad_u64_u32 v[152:153], s[10:11], v153, s6, v[146:147]
	v_mov_b32_e32 v149, v152
	v_mov_b32_e32 v146, v147
	v_lshl_add_u64 v[150:151], v[150:151], 1, v[148:149]
	global_store_dwordx4 v[150:151], v[160:163], off
	v_mul_f32_e32 v184, 0xbfb8aa3b, v146
	v_mul_f32_e32 v206, v146, v146
	v_pk_mul_f32 v[168:169], v[116:117], v[184:185] op_sel_hi:[1,0]
	v_pk_mul_f32 v[170:171], v[118:119], v[184:185] op_sel_hi:[1,0]
	v_pk_mul_f32 v[172:173], v[112:113], v[184:185] op_sel_hi:[1,0]
	v_pk_mul_f32 v[174:175], v[114:115], v[184:185] op_sel_hi:[1,0]
	v_exp_f32_e32 v168, v168
	v_exp_f32_e32 v169, v169
	v_exp_f32_e32 v170, v170
	v_exp_f32_e32 v171, v171
	v_exp_f32_e32 v172, v172
	v_exp_f32_e32 v173, v173
	v_exp_f32_e32 v174, v174
	v_exp_f32_e32 v175, v175
	v_pk_mul_f32 v[176:177], v[116:117], v[84:85]
	v_pk_mul_f32 v[178:179], v[118:119], v[86:87]
	v_pk_mul_f32 v[180:181], v[112:113], v[80:81]
	v_pk_mul_f32 v[182:183], v[114:115], v[82:83]
	v_pk_add_f32 v[168:169], v[168:169], 1.0 op_sel_hi:[1,0]
	v_pk_add_f32 v[170:171], v[170:171], 1.0 op_sel_hi:[1,0]
	v_pk_add_f32 v[172:173], v[172:173], 1.0 op_sel_hi:[1,0]
	v_pk_add_f32 v[174:175], v[174:175], 1.0 op_sel_hi:[1,0]
	v_rcp_f32_e32 v168, v168
	v_rcp_f32_e32 v169, v169
	v_rcp_f32_e32 v170, v170
	v_rcp_f32_e32 v171, v171
	v_rcp_f32_e32 v172, v172
	v_rcp_f32_e32 v173, v173
	v_rcp_f32_e32 v174, v174
	v_rcp_f32_e32 v175, v175
	v_pk_mul_f32 v[176:177], v[176:177], v[206:207] op_sel_hi:[1,0]
	v_pk_mul_f32 v[178:179], v[178:179], v[206:207] op_sel_hi:[1,0]
	v_pk_mul_f32 v[180:181], v[180:181], v[206:207] op_sel_hi:[1,0]
	v_pk_mul_f32 v[182:183], v[182:183], v[206:207] op_sel_hi:[1,0]
	v_pk_mul_f32 v[176:177], v[176:177], v[168:169]
	v_pk_mul_f32 v[178:179], v[178:179], v[170:171]
	v_pk_mul_f32 v[180:181], v[180:181], v[172:173]
	v_pk_mul_f32 v[182:183], v[182:183], v[174:175]
	v_cvt_pk_bf16_f32 v160, v176, v177
	v_cvt_pk_bf16_f32 v161, v178, v179
	v_cvt_pk_bf16_f32 v162, v180, v181
	v_cvt_pk_bf16_f32 v163, v182, v183
	s_mov_b32 s6, 0x16000
	s_mov_b64 s[10:11], 0x16000
	s_nop 1
	v_lshl_add_u64 v[146:147], v[150:151], 0, s[10:11]
	global_store_dwordx4 v[146:147], v[160:163], off
	v_mov_b32_e32 v146, v208
	v_mov_b32_e32 v147, v209
	s_mov_b32 s6, 0x2c000
	s_waitcnt lgkmcnt(0)
	v_mul_f32_e32 v184, 0xbfb8aa3b, v146
	v_mul_f32_e32 v206, v146, v146
	v_pk_mul_f32 v[168:169], v[108:109], v[184:185] op_sel_hi:[1,0]
	v_pk_mul_f32 v[170:171], v[110:111], v[184:185] op_sel_hi:[1,0]
	v_pk_mul_f32 v[172:173], v[104:105], v[184:185] op_sel_hi:[1,0]
	v_pk_mul_f32 v[174:175], v[106:107], v[184:185] op_sel_hi:[1,0]
	v_exp_f32_e32 v168, v168
	v_exp_f32_e32 v169, v169
	v_exp_f32_e32 v170, v170
	v_exp_f32_e32 v171, v171
	v_exp_f32_e32 v172, v172
	v_exp_f32_e32 v173, v173
	v_exp_f32_e32 v174, v174
	v_exp_f32_e32 v175, v175
	v_pk_mul_f32 v[176:177], v[108:109], v[76:77]
	v_pk_mul_f32 v[178:179], v[110:111], v[78:79]
	v_pk_mul_f32 v[180:181], v[104:105], v[72:73]
	v_pk_mul_f32 v[182:183], v[106:107], v[74:75]
	v_pk_add_f32 v[168:169], v[168:169], 1.0 op_sel_hi:[1,0]
	v_pk_add_f32 v[170:171], v[170:171], 1.0 op_sel_hi:[1,0]
	v_pk_add_f32 v[172:173], v[172:173], 1.0 op_sel_hi:[1,0]
	v_pk_add_f32 v[174:175], v[174:175], 1.0 op_sel_hi:[1,0]
	v_rcp_f32_e32 v168, v168
	v_rcp_f32_e32 v169, v169
	v_rcp_f32_e32 v170, v170
	v_rcp_f32_e32 v171, v171
	v_rcp_f32_e32 v172, v172
	v_rcp_f32_e32 v173, v173
	v_rcp_f32_e32 v174, v174
	v_rcp_f32_e32 v175, v175
	v_pk_mul_f32 v[176:177], v[176:177], v[206:207] op_sel_hi:[1,0]
	v_pk_mul_f32 v[178:179], v[178:179], v[206:207] op_sel_hi:[1,0]
	v_pk_mul_f32 v[180:181], v[180:181], v[206:207] op_sel_hi:[1,0]
	v_pk_mul_f32 v[182:183], v[182:183], v[206:207] op_sel_hi:[1,0]
	v_pk_mul_f32 v[176:177], v[176:177], v[168:169]
	v_pk_mul_f32 v[178:179], v[178:179], v[170:171]
	v_pk_mul_f32 v[180:181], v[180:181], v[172:173]
	v_pk_mul_f32 v[182:183], v[182:183], v[174:175]
	v_cvt_pk_bf16_f32 v160, v176, v177
	v_cvt_pk_bf16_f32 v161, v178, v179
	v_cvt_pk_bf16_f32 v162, v180, v181
	v_cvt_pk_bf16_f32 v163, v182, v183
	s_nop 1
	v_mov_b32_e32 v146, v147
	s_mov_b64 s[10:11], 0x2c000
	v_lshl_add_u64 v[148:149], v[150:151], 0, s[10:11]
	global_store_dwordx4 v[148:149], v[160:163], off
	v_mul_f32_e32 v184, 0xbfb8aa3b, v146
	v_mul_f32_e32 v206, v146, v146
	v_pk_mul_f32 v[168:169], v[100:101], v[184:185] op_sel_hi:[1,0]
	v_pk_mul_f32 v[170:171], v[102:103], v[184:185] op_sel_hi:[1,0]
	v_pk_mul_f32 v[172:173], v[96:97], v[184:185] op_sel_hi:[1,0]
	v_pk_mul_f32 v[174:175], v[98:99], v[184:185] op_sel_hi:[1,0]
	v_exp_f32_e32 v168, v168
	v_exp_f32_e32 v169, v169
	v_exp_f32_e32 v170, v170
	v_exp_f32_e32 v171, v171
	v_exp_f32_e32 v172, v172
	v_exp_f32_e32 v173, v173
	v_exp_f32_e32 v174, v174
	v_exp_f32_e32 v175, v175
	v_pk_mul_f32 v[176:177], v[100:101], v[68:69]
	v_pk_mul_f32 v[178:179], v[102:103], v[70:71]
	v_pk_mul_f32 v[180:181], v[96:97], v[64:65]
	v_pk_mul_f32 v[182:183], v[98:99], v[66:67]
	v_pk_add_f32 v[168:169], v[168:169], 1.0 op_sel_hi:[1,0]
	v_pk_add_f32 v[170:171], v[170:171], 1.0 op_sel_hi:[1,0]
	v_pk_add_f32 v[172:173], v[172:173], 1.0 op_sel_hi:[1,0]
	v_pk_add_f32 v[174:175], v[174:175], 1.0 op_sel_hi:[1,0]
	v_rcp_f32_e32 v168, v168
	v_rcp_f32_e32 v169, v169
	v_rcp_f32_e32 v170, v170
	v_rcp_f32_e32 v171, v171
	v_rcp_f32_e32 v172, v172
	v_rcp_f32_e32 v173, v173
	v_rcp_f32_e32 v174, v174
	v_rcp_f32_e32 v175, v175
	v_pk_mul_f32 v[176:177], v[176:177], v[206:207] op_sel_hi:[1,0]
	v_pk_mul_f32 v[178:179], v[178:179], v[206:207] op_sel_hi:[1,0]
	v_pk_mul_f32 v[180:181], v[180:181], v[206:207] op_sel_hi:[1,0]
	v_pk_mul_f32 v[182:183], v[182:183], v[206:207] op_sel_hi:[1,0]
	v_pk_mul_f32 v[176:177], v[176:177], v[168:169]
	v_pk_mul_f32 v[178:179], v[178:179], v[170:171]
	v_pk_mul_f32 v[180:181], v[180:181], v[172:173]
	v_pk_mul_f32 v[182:183], v[182:183], v[174:175]
	v_cvt_pk_bf16_f32 v160, v176, v177
	v_cvt_pk_bf16_f32 v161, v178, v179
	v_cvt_pk_bf16_f32 v162, v180, v181
	v_cvt_pk_bf16_f32 v163, v182, v183
	s_mov_b32 s6, 0x42000
	s_mov_b64 s[10:11], 0x42000
	s_nop 1
	v_lshl_add_u64 v[146:147], v[150:151], 0, s[10:11]
	global_store_dwordx4 v[146:147], v[160:163], off
	v_mov_b32_e32 v146, v210
	v_mov_b32_e32 v147, v211
	s_mov_b32 s6, 0xb0000
	s_waitcnt lgkmcnt(0)
	v_mul_f32_e32 v184, 0xbfb8aa3b, v146
	v_mul_f32_e32 v206, v146, v146
	v_pk_mul_f32 v[168:169], v[60:61], v[184:185] op_sel_hi:[1,0]
	v_pk_mul_f32 v[170:171], v[62:63], v[184:185] op_sel_hi:[1,0]
	v_pk_mul_f32 v[172:173], v[56:57], v[184:185] op_sel_hi:[1,0]
	v_pk_mul_f32 v[174:175], v[58:59], v[184:185] op_sel_hi:[1,0]
	v_exp_f32_e32 v168, v168
	v_exp_f32_e32 v169, v169
	v_exp_f32_e32 v170, v170
	v_exp_f32_e32 v171, v171
	v_exp_f32_e32 v172, v172
	v_exp_f32_e32 v173, v173
	v_exp_f32_e32 v174, v174
	v_exp_f32_e32 v175, v175
	v_pk_mul_f32 v[176:177], v[60:61], v[28:29]
	v_pk_mul_f32 v[178:179], v[62:63], v[30:31]
	v_pk_mul_f32 v[180:181], v[56:57], v[24:25]
	v_pk_mul_f32 v[182:183], v[58:59], v[26:27]
	v_pk_add_f32 v[168:169], v[168:169], 1.0 op_sel_hi:[1,0]
	v_pk_add_f32 v[170:171], v[170:171], 1.0 op_sel_hi:[1,0]
	v_pk_add_f32 v[172:173], v[172:173], 1.0 op_sel_hi:[1,0]
	v_pk_add_f32 v[174:175], v[174:175], 1.0 op_sel_hi:[1,0]
	v_rcp_f32_e32 v168, v168
	v_rcp_f32_e32 v169, v169
	v_rcp_f32_e32 v170, v170
	v_rcp_f32_e32 v171, v171
	v_rcp_f32_e32 v172, v172
	v_rcp_f32_e32 v173, v173
	v_rcp_f32_e32 v174, v174
	v_rcp_f32_e32 v175, v175
	v_pk_mul_f32 v[176:177], v[176:177], v[206:207] op_sel_hi:[1,0]
	v_pk_mul_f32 v[178:179], v[178:179], v[206:207] op_sel_hi:[1,0]
	v_pk_mul_f32 v[180:181], v[180:181], v[206:207] op_sel_hi:[1,0]
	v_pk_mul_f32 v[182:183], v[182:183], v[206:207] op_sel_hi:[1,0]
	v_pk_mul_f32 v[176:177], v[176:177], v[168:169]
	v_pk_mul_f32 v[178:179], v[178:179], v[170:171]
	v_pk_mul_f32 v[180:181], v[180:181], v[172:173]
	v_pk_mul_f32 v[182:183], v[182:183], v[174:175]
	v_cvt_pk_bf16_f32 v160, v176, v177
	v_cvt_pk_bf16_f32 v161, v178, v179
	v_cvt_pk_bf16_f32 v162, v180, v181
	v_cvt_pk_bf16_f32 v163, v182, v183
	s_nop 1
	v_mov_b32_e32 v146, v147
	s_mov_b64 s[10:11], 0xb0000
	v_lshl_add_u64 v[148:149], v[150:151], 0, s[10:11]
	global_store_dwordx4 v[148:149], v[160:163], off
	v_mul_f32_e32 v184, 0xbfb8aa3b, v146
	v_mul_f32_e32 v206, v146, v146
	v_pk_mul_f32 v[168:169], v[52:53], v[184:185] op_sel_hi:[1,0]
	v_pk_mul_f32 v[170:171], v[54:55], v[184:185] op_sel_hi:[1,0]
	v_pk_mul_f32 v[172:173], v[48:49], v[184:185] op_sel_hi:[1,0]
	v_pk_mul_f32 v[174:175], v[50:51], v[184:185] op_sel_hi:[1,0]
	v_exp_f32_e32 v168, v168
	v_exp_f32_e32 v169, v169
	v_exp_f32_e32 v170, v170
	v_exp_f32_e32 v171, v171
	v_exp_f32_e32 v172, v172
	v_exp_f32_e32 v173, v173
	v_exp_f32_e32 v174, v174
	v_exp_f32_e32 v175, v175
	v_pk_mul_f32 v[176:177], v[52:53], v[20:21]
	v_pk_mul_f32 v[178:179], v[54:55], v[22:23]
	v_pk_mul_f32 v[180:181], v[48:49], v[16:17]
	v_pk_mul_f32 v[182:183], v[50:51], v[18:19]
	v_pk_add_f32 v[168:169], v[168:169], 1.0 op_sel_hi:[1,0]
	v_pk_add_f32 v[170:171], v[170:171], 1.0 op_sel_hi:[1,0]
	v_pk_add_f32 v[172:173], v[172:173], 1.0 op_sel_hi:[1,0]
	v_pk_add_f32 v[174:175], v[174:175], 1.0 op_sel_hi:[1,0]
	v_rcp_f32_e32 v168, v168
	v_rcp_f32_e32 v169, v169
	v_rcp_f32_e32 v170, v170
	v_rcp_f32_e32 v171, v171
	v_rcp_f32_e32 v172, v172
	v_rcp_f32_e32 v173, v173
	v_rcp_f32_e32 v174, v174
	v_rcp_f32_e32 v175, v175
	v_pk_mul_f32 v[176:177], v[176:177], v[206:207] op_sel_hi:[1,0]
	v_pk_mul_f32 v[178:179], v[178:179], v[206:207] op_sel_hi:[1,0]
	v_pk_mul_f32 v[180:181], v[180:181], v[206:207] op_sel_hi:[1,0]
	v_pk_mul_f32 v[182:183], v[182:183], v[206:207] op_sel_hi:[1,0]
	v_pk_mul_f32 v[176:177], v[176:177], v[168:169]
	v_pk_mul_f32 v[178:179], v[178:179], v[170:171]
	v_pk_mul_f32 v[180:181], v[180:181], v[172:173]
	v_pk_mul_f32 v[182:183], v[182:183], v[174:175]
	v_cvt_pk_bf16_f32 v160, v176, v177
	v_cvt_pk_bf16_f32 v161, v178, v179
	v_cvt_pk_bf16_f32 v162, v180, v181
	v_cvt_pk_bf16_f32 v163, v182, v183
	s_mov_b32 s6, 0xc6000
	s_mov_b64 s[10:11], 0xc6000
	s_nop 1
	v_lshl_add_u64 v[146:147], v[150:151], 0, s[10:11]
	global_store_dwordx4 v[146:147], v[160:163], off
	v_mov_b32_e32 v146, v212
	v_mov_b32_e32 v147, v213
	s_mov_b32 s6, 0xdc000
	s_waitcnt lgkmcnt(0)
	v_mul_f32_e32 v184, 0xbfb8aa3b, v146
	v_mul_f32_e32 v206, v146, v146
	v_pk_mul_f32 v[168:169], v[44:45], v[184:185] op_sel_hi:[1,0]
	v_pk_mul_f32 v[170:171], v[46:47], v[184:185] op_sel_hi:[1,0]
	v_pk_mul_f32 v[172:173], v[40:41], v[184:185] op_sel_hi:[1,0]
	v_pk_mul_f32 v[174:175], v[42:43], v[184:185] op_sel_hi:[1,0]
	v_exp_f32_e32 v168, v168
	v_exp_f32_e32 v169, v169
	v_exp_f32_e32 v170, v170
	v_exp_f32_e32 v171, v171
	v_exp_f32_e32 v172, v172
	v_exp_f32_e32 v173, v173
	v_exp_f32_e32 v174, v174
	v_exp_f32_e32 v175, v175
	v_pk_mul_f32 v[176:177], v[44:45], v[12:13]
	v_pk_mul_f32 v[178:179], v[46:47], v[14:15]
	v_pk_mul_f32 v[180:181], v[40:41], v[8:9]
	v_pk_mul_f32 v[182:183], v[42:43], v[10:11]
	v_pk_add_f32 v[168:169], v[168:169], 1.0 op_sel_hi:[1,0]
	v_pk_add_f32 v[170:171], v[170:171], 1.0 op_sel_hi:[1,0]
	v_pk_add_f32 v[172:173], v[172:173], 1.0 op_sel_hi:[1,0]
	v_pk_add_f32 v[174:175], v[174:175], 1.0 op_sel_hi:[1,0]
	v_rcp_f32_e32 v168, v168
	v_rcp_f32_e32 v169, v169
	v_rcp_f32_e32 v170, v170
	v_rcp_f32_e32 v171, v171
	v_rcp_f32_e32 v172, v172
	v_rcp_f32_e32 v173, v173
	v_rcp_f32_e32 v174, v174
	v_rcp_f32_e32 v175, v175
	v_pk_mul_f32 v[176:177], v[176:177], v[206:207] op_sel_hi:[1,0]
	v_pk_mul_f32 v[178:179], v[178:179], v[206:207] op_sel_hi:[1,0]
	v_pk_mul_f32 v[180:181], v[180:181], v[206:207] op_sel_hi:[1,0]
	v_pk_mul_f32 v[182:183], v[182:183], v[206:207] op_sel_hi:[1,0]
	v_pk_mul_f32 v[176:177], v[176:177], v[168:169]
	v_pk_mul_f32 v[178:179], v[178:179], v[170:171]
	v_pk_mul_f32 v[180:181], v[180:181], v[172:173]
	v_pk_mul_f32 v[182:183], v[182:183], v[174:175]
	v_cvt_pk_bf16_f32 v158, v176, v177
	v_cvt_pk_bf16_f32 v159, v178, v179
	v_cvt_pk_bf16_f32 v160, v180, v181
	v_cvt_pk_bf16_f32 v161, v182, v183
	s_nop 1
	v_mov_b32_e32 v146, v147
	s_mov_b64 s[10:11], 0xdc000
	v_lshl_add_u64 v[148:149], v[150:151], 0, s[10:11]
	global_store_dwordx4 v[148:149], v[158:161], off
	v_mul_f32_e32 v184, 0xbfb8aa3b, v146
	v_mul_f32_e32 v206, v146, v146
	v_pk_mul_f32 v[168:169], v[36:37], v[184:185] op_sel_hi:[1,0]
	v_pk_mul_f32 v[170:171], v[38:39], v[184:185] op_sel_hi:[1,0]
	v_pk_mul_f32 v[172:173], v[32:33], v[184:185] op_sel_hi:[1,0]
	v_pk_mul_f32 v[174:175], v[34:35], v[184:185] op_sel_hi:[1,0]
	v_exp_f32_e32 v168, v168
	v_exp_f32_e32 v169, v169
	v_exp_f32_e32 v170, v170
	v_exp_f32_e32 v171, v171
	v_exp_f32_e32 v172, v172
	v_exp_f32_e32 v173, v173
	v_exp_f32_e32 v174, v174
	v_exp_f32_e32 v175, v175
	v_pk_mul_f32 v[176:177], v[36:37], v[4:5]
	v_pk_mul_f32 v[178:179], v[38:39], v[6:7]
	v_pk_mul_f32 v[180:181], v[32:33], v[0:1]
	v_pk_mul_f32 v[182:183], v[34:35], v[2:3]
	v_pk_add_f32 v[168:169], v[168:169], 1.0 op_sel_hi:[1,0]
	v_pk_add_f32 v[170:171], v[170:171], 1.0 op_sel_hi:[1,0]
	v_pk_add_f32 v[172:173], v[172:173], 1.0 op_sel_hi:[1,0]
	v_pk_add_f32 v[174:175], v[174:175], 1.0 op_sel_hi:[1,0]
	v_rcp_f32_e32 v168, v168
	v_rcp_f32_e32 v169, v169
	v_rcp_f32_e32 v170, v170
	v_rcp_f32_e32 v171, v171
	v_rcp_f32_e32 v172, v172
	v_rcp_f32_e32 v173, v173
	v_rcp_f32_e32 v174, v174
	v_rcp_f32_e32 v175, v175
	v_pk_mul_f32 v[176:177], v[176:177], v[206:207] op_sel_hi:[1,0]
	v_pk_mul_f32 v[178:179], v[178:179], v[206:207] op_sel_hi:[1,0]
	v_pk_mul_f32 v[180:181], v[180:181], v[206:207] op_sel_hi:[1,0]
	v_pk_mul_f32 v[182:183], v[182:183], v[206:207] op_sel_hi:[1,0]
	v_pk_mul_f32 v[176:177], v[176:177], v[168:169]
	v_pk_mul_f32 v[178:179], v[178:179], v[170:171]
	v_pk_mul_f32 v[180:181], v[180:181], v[172:173]
	v_pk_mul_f32 v[182:183], v[182:183], v[174:175]
	v_cvt_pk_bf16_f32 v158, v176, v177
	v_cvt_pk_bf16_f32 v159, v178, v179
	v_cvt_pk_bf16_f32 v160, v180, v181
	v_cvt_pk_bf16_f32 v161, v182, v183
	s_mov_b64 s[10:11], 0xf2000
	s_nop 1
	v_lshl_add_u64 v[146:147], v[150:151], 0, s[10:11]
	s_andn2_b64 vcc, exec, s[44:45]
	global_store_dwordx4 v[146:147], v[158:161], off
	s_cbranch_vccz .LBB0_382
	s_mov_b64 s[48:49], s[52:53]
	s_andn2_b64 vcc, exec, s[42:43]
	s_mov_b64 s[52:53], s[48:49]
	s_cbranch_vccnz .LBB0_383
